# P0 weight transpose rewritten: register-only transpose, dwordx4 loads, double-buffered (no LDS)
# speedup vs baseline: 1.0020x; 1.0020x over previous
.LBB0_5:
	s_or_b64 exec, exec, s[4:5]
	s_lshr_b32 s4, s8, 6
	s_load_dwordx2 s[8:9], s[0:1], 0x50
	v_readlane_b32 s5, v255, 0
	s_lshl_b32 s5, s5, 3
	s_add_i32 s6, s4, s5
	s_load_dwordx16 s[80:95], s[0:1], 0x0
	s_waitcnt lgkmcnt(0)
	s_lshl_b32 s8, s8, 3
	s_add_u32 s5, s56, 0x100000
	v_writelane_b32 v255, s5, 6
	s_addc_u32 s5, s57, 0
	v_writelane_b32 v255, s5, 7
	s_add_u32 s5, s56, 0x8100000
	v_writelane_b32 v255, s5, 8
	s_addc_u32 s5, s57, 0
	v_writelane_b32 v255, s5, 9
	s_cmp_gt_i32 s6, 0x9fff
	v_and_b32_e32 v1, 63, v243
	s_cbranch_scc1 .LBB0_20
	v_lshrrev_b32_e32 v6, 3, v1
	v_and_b32_e32 v7, 7, v1
	v_lshlrev_b32_e32 v8, 4, v7
	v_lshl_or_b32 v2, v6, 18, v8
	v_lshl_or_b32 v3, v6, 16, v8
	v_lshlrev_b32_e32 v4, 5, v6
	v_lshlrev_b32_e32 v9, 4, v6
	v_lshl_or_b32 v5, v7, 14, v9
	v_readlane_b32 s40, v255, 6
	v_readlane_b32 s41, v255, 7
	v_readlane_b32 s42, v255, 8
	v_readlane_b32 s43, v255, 9
	s_mov_b32 s7, s6
	s_mul_hi_u32 s9, s7, 0x66666667
	s_lshr_b32 s9, s9, 12
	s_mul_i32 s10, s9, 0x2800
	s_sub_u32 s10, s7, s10
	s_sub_u32 s9, 3, s9
	s_cmp_lt_u32 s10, 0x2000
	s_cselect_b64 s[12:13], -1, 0
	s_cselect_b32 s11, 0, 0x2000
	s_cselect_b32 s14, 7, 5
	s_cselect_b32 s15, 15, 13
	s_cselect_b32 s16, 26, 24
	s_cselect_b32 s17, 25, 23
	s_cselect_b32 s20, s84, s92
	s_cselect_b32 s21, s85, s93
	s_cselect_b32 s22, s40, s42
	s_cselect_b32 s23, s41, s43
	s_sub_u32 s10, s10, s11
	s_lshr_b32 s24, s10, 3
	s_lshr_b32 s25, s24, s14
	s_lshl_b32 s26, s25, s14
	s_sub_u32 s24, s24, s26
	s_and_b32 s26, s10, 1
	s_lshl_b32 s24, s24, 1
	s_or_b32 s24, s24, s26
	s_bfe_u32 s26, s10, 0x20001
	s_lshl_b32 s25, s25, 2
	s_or_b32 s25, s25, s26
	s_lshl_b32 s25, s25, 6
	s_lshl_b32 s24, s24, 5
	s_lshl_b32 s26, s9, s16
	s_lshl_b32 s27, s25, s15
	s_add_u32 s26, s26, s27
	s_lshl_b32 s27, s24, 2
	s_add_u32 s26, s26, s27
	s_add_u32 s20, s20, s26
	s_addc_u32 s21, s21, 0
	s_lshl_b32 s28, 1, s15
	s_lshl_b32 s26, s9, s17
	s_lshl_b32 s27, s24, 12
	s_add_u32 s26, s26, s27
	s_lshl_b32 s27, s25, 1
	s_add_u32 s26, s26, s27
	s_add_u32 s22, s22, s26
	s_addc_u32 s23, s23, 0
	s_lshl_b32 s26, s9, 13
	s_lshl_b32 s27, s25, 2
	s_add_u32 s26, s26, s27
	s_add_u32 s30, s82, s26
	s_addc_u32 s31, s83, 0
	v_cndmask_b32_e64 v6, v3, v2, s[12:13]
	global_load_dwordx4 v[48:51], v4, s[30:31]
	global_load_dwordx4 v[52:55], v4, s[30:31] offset:16
	global_load_dwordx4 v[16:19], v6, s[20:21] nt
	s_add_u32 s20, s20, s28
	s_addc_u32 s21, s21, 0
	global_load_dwordx4 v[20:23], v6, s[20:21] nt
	s_add_u32 s20, s20, s28
	s_addc_u32 s21, s21, 0
	global_load_dwordx4 v[24:27], v6, s[20:21] nt
	s_add_u32 s20, s20, s28
	s_addc_u32 s21, s21, 0
	global_load_dwordx4 v[28:31], v6, s[20:21] nt
	s_add_u32 s20, s20, s28
	s_addc_u32 s21, s21, 0
	global_load_dwordx4 v[32:35], v6, s[20:21] nt
	s_add_u32 s20, s20, s28
	s_addc_u32 s21, s21, 0
	global_load_dwordx4 v[36:39], v6, s[20:21] nt
	s_add_u32 s20, s20, s28
	s_addc_u32 s21, s21, 0
	global_load_dwordx4 v[40:43], v6, s[20:21] nt
	s_add_u32 s20, s20, s28
	s_addc_u32 s21, s21, 0
	global_load_dwordx4 v[44:47], v6, s[20:21] nt
	s_add_u32 s46, s7, s8
	s_cmp_lt_u32 s46, 0xa000
	s_cbranch_scc0 .Lp0_nob0
	s_mul_hi_u32 s9, s46, 0x66666667
	s_lshr_b32 s9, s9, 12
	s_mul_i32 s10, s9, 0x2800
	s_sub_u32 s10, s46, s10
	s_sub_u32 s9, 3, s9
	s_cmp_lt_u32 s10, 0x2000
	s_cselect_b64 s[32:33], -1, 0
	s_cselect_b32 s11, 0, 0x2000
	s_cselect_b32 s14, 7, 5
	s_cselect_b32 s15, 15, 13
	s_cselect_b32 s16, 26, 24
	s_cselect_b32 s17, 25, 23
	s_cselect_b32 s38, s84, s92
	s_cselect_b32 s39, s85, s93
	s_cselect_b32 s34, s40, s42
	s_cselect_b32 s35, s41, s43
	s_sub_u32 s10, s10, s11
	s_lshr_b32 s24, s10, 3
	s_lshr_b32 s25, s24, s14
	s_lshl_b32 s26, s25, s14
	s_sub_u32 s24, s24, s26
	s_and_b32 s26, s10, 1
	s_lshl_b32 s24, s24, 1
	s_or_b32 s24, s24, s26
	s_bfe_u32 s26, s10, 0x20001
	s_lshl_b32 s25, s25, 2
	s_or_b32 s25, s25, s26
	s_lshl_b32 s25, s25, 6
	s_lshl_b32 s24, s24, 5
	s_lshl_b32 s26, s9, s16
	s_lshl_b32 s27, s25, s15
	s_add_u32 s26, s26, s27
	s_lshl_b32 s27, s24, 2
	s_add_u32 s26, s26, s27
	s_add_u32 s38, s38, s26
	s_addc_u32 s39, s39, 0
	s_lshl_b32 s29, 1, s15
	s_lshl_b32 s26, s9, s17
	s_lshl_b32 s27, s24, 12
	s_add_u32 s26, s26, s27
	s_lshl_b32 s27, s25, 1
	s_add_u32 s26, s26, s27
	s_add_u32 s34, s34, s26
	s_addc_u32 s35, s35, 0
	s_lshl_b32 s26, s9, 13
	s_lshl_b32 s27, s25, 2
	s_add_u32 s26, s26, s27
	s_add_u32 s44, s82, s26
	s_addc_u32 s45, s83, 0
	v_cndmask_b32_e64 v7, v3, v2, s[32:33]
	global_load_dwordx4 v[96:99], v4, s[44:45]
	global_load_dwordx4 v[100:103], v4, s[44:45] offset:16
	global_load_dwordx4 v[64:67], v7, s[38:39] nt
	s_add_u32 s38, s38, s29
	s_addc_u32 s39, s39, 0
	global_load_dwordx4 v[68:71], v7, s[38:39] nt
	s_add_u32 s38, s38, s29
	s_addc_u32 s39, s39, 0
	global_load_dwordx4 v[72:75], v7, s[38:39] nt
	s_add_u32 s38, s38, s29
	s_addc_u32 s39, s39, 0
	global_load_dwordx4 v[76:79], v7, s[38:39] nt
	s_add_u32 s38, s38, s29
	s_addc_u32 s39, s39, 0
	global_load_dwordx4 v[80:83], v7, s[38:39] nt
	s_add_u32 s38, s38, s29
	s_addc_u32 s39, s39, 0
	global_load_dwordx4 v[84:87], v7, s[38:39] nt
	s_add_u32 s38, s38, s29
	s_addc_u32 s39, s39, 0
	global_load_dwordx4 v[88:91], v7, s[38:39] nt
	s_add_u32 s38, s38, s29
	s_addc_u32 s39, s39, 0
	global_load_dwordx4 v[92:95], v7, s[38:39] nt
	s_waitcnt vmcnt(10)
	s_branch .Lp0_loop

.Lp0_loop:
	s_cmp_eq_u64 s[12:13], 0
	s_cbranch_scc1 .Lp0_nomul_a
	v_mul_f32_e32 v16, v16, v48
	v_mul_f32_e32 v17, v17, v48
	v_mul_f32_e32 v18, v18, v48
	v_mul_f32_e32 v19, v19, v48
	v_mul_f32_e32 v20, v20, v49
	v_mul_f32_e32 v21, v21, v49
	v_mul_f32_e32 v22, v22, v49
	v_mul_f32_e32 v23, v23, v49
	v_mul_f32_e32 v24, v24, v50
	v_mul_f32_e32 v25, v25, v50
	v_mul_f32_e32 v26, v26, v50
	v_mul_f32_e32 v27, v27, v50
	v_mul_f32_e32 v28, v28, v51
	v_mul_f32_e32 v29, v29, v51
	v_mul_f32_e32 v30, v30, v51
	v_mul_f32_e32 v31, v31, v51
	v_mul_f32_e32 v32, v32, v52
	v_mul_f32_e32 v33, v33, v52
	v_mul_f32_e32 v34, v34, v52
	v_mul_f32_e32 v35, v35, v52
	v_mul_f32_e32 v36, v36, v53
	v_mul_f32_e32 v37, v37, v53
	v_mul_f32_e32 v38, v38, v53
	v_mul_f32_e32 v39, v39, v53
	v_mul_f32_e32 v40, v40, v54
	v_mul_f32_e32 v41, v41, v54
	v_mul_f32_e32 v42, v42, v54
	v_mul_f32_e32 v43, v43, v54
	v_mul_f32_e32 v44, v44, v55
	v_mul_f32_e32 v45, v45, v55
	v_mul_f32_e32 v46, v46, v55
	v_mul_f32_e32 v47, v47, v55
.Lp0_nomul_a:
	v_cvt_pk_bf16_f32 v112, v16, v20
	v_cvt_pk_bf16_f32 v113, v24, v28
	v_cvt_pk_bf16_f32 v114, v32, v36
	v_cvt_pk_bf16_f32 v115, v40, v44
	v_cvt_pk_bf16_f32 v116, v17, v21
	v_cvt_pk_bf16_f32 v117, v25, v29
	v_cvt_pk_bf16_f32 v118, v33, v37
	v_cvt_pk_bf16_f32 v119, v41, v45
	v_cvt_pk_bf16_f32 v120, v18, v22
	v_cvt_pk_bf16_f32 v121, v26, v30
	v_cvt_pk_bf16_f32 v122, v34, v38
	v_cvt_pk_bf16_f32 v123, v42, v46
	v_cvt_pk_bf16_f32 v124, v19, v23
	v_cvt_pk_bf16_f32 v125, v27, v31
	v_cvt_pk_bf16_f32 v126, v35, v39
	v_cvt_pk_bf16_f32 v127, v43, v47
	global_store_dwordx4 v5, v[112:115], s[22:23]
	s_add_u32 s22, s22, 0x1000
	s_addc_u32 s23, s23, 0
	global_store_dwordx4 v5, v[116:119], s[22:23]
	s_add_u32 s22, s22, 0x1000
	s_addc_u32 s23, s23, 0
	global_store_dwordx4 v5, v[120:123], s[22:23]
	s_add_u32 s22, s22, 0x1000
	s_addc_u32 s23, s23, 0
	global_store_dwordx4 v5, v[124:127], s[22:23]
	s_add_u32 s7, s46, s8
	s_cmp_lt_u32 s46, 0xa000
	s_cbranch_scc0 .Lp0_done
	s_cmp_lt_u32 s7, 0xa000
	s_cbranch_scc0 .Lp0_noa
	s_mul_hi_u32 s9, s7, 0x66666667
	s_lshr_b32 s9, s9, 12
	s_mul_i32 s10, s9, 0x2800
	s_sub_u32 s10, s7, s10
	s_sub_u32 s9, 3, s9
	s_cmp_lt_u32 s10, 0x2000
	s_cselect_b64 s[12:13], -1, 0
	s_cselect_b32 s11, 0, 0x2000
	s_cselect_b32 s14, 7, 5
	s_cselect_b32 s15, 15, 13
	s_cselect_b32 s16, 26, 24
	s_cselect_b32 s17, 25, 23
	s_cselect_b32 s20, s84, s92
	s_cselect_b32 s21, s85, s93
	s_cselect_b32 s22, s40, s42
	s_cselect_b32 s23, s41, s43
	s_sub_u32 s10, s10, s11
	s_lshr_b32 s24, s10, 3
	s_lshr_b32 s25, s24, s14
	s_lshl_b32 s26, s25, s14
	s_sub_u32 s24, s24, s26
	s_and_b32 s26, s10, 1
	s_lshl_b32 s24, s24, 1
	s_or_b32 s24, s24, s26
	s_bfe_u32 s26, s10, 0x20001
	s_lshl_b32 s25, s25, 2
	s_or_b32 s25, s25, s26
	s_lshl_b32 s25, s25, 6
	s_lshl_b32 s24, s24, 5
	s_lshl_b32 s26, s9, s16
	s_lshl_b32 s27, s25, s15
	s_add_u32 s26, s26, s27
	s_lshl_b32 s27, s24, 2
	s_add_u32 s26, s26, s27
	s_add_u32 s20, s20, s26
	s_addc_u32 s21, s21, 0
	s_lshl_b32 s28, 1, s15
	s_lshl_b32 s26, s9, s17
	s_lshl_b32 s27, s24, 12
	s_add_u32 s26, s26, s27
	s_lshl_b32 s27, s25, 1
	s_add_u32 s26, s26, s27
	s_add_u32 s22, s22, s26
	s_addc_u32 s23, s23, 0
	s_lshl_b32 s26, s9, 13
	s_lshl_b32 s27, s25, 2
	s_add_u32 s26, s26, s27
	s_add_u32 s30, s82, s26
	s_addc_u32 s31, s83, 0
	v_cndmask_b32_e64 v6, v3, v2, s[12:13]
	global_load_dwordx4 v[48:51], v4, s[30:31]
	global_load_dwordx4 v[52:55], v4, s[30:31] offset:16
	global_load_dwordx4 v[16:19], v6, s[20:21] nt
	s_add_u32 s20, s20, s28
	s_addc_u32 s21, s21, 0
	global_load_dwordx4 v[20:23], v6, s[20:21] nt
	s_add_u32 s20, s20, s28
	s_addc_u32 s21, s21, 0
	global_load_dwordx4 v[24:27], v6, s[20:21] nt
	s_add_u32 s20, s20, s28
	s_addc_u32 s21, s21, 0
	global_load_dwordx4 v[28:31], v6, s[20:21] nt
	s_add_u32 s20, s20, s28
	s_addc_u32 s21, s21, 0
	global_load_dwordx4 v[32:35], v6, s[20:21] nt
	s_add_u32 s20, s20, s28
	s_addc_u32 s21, s21, 0
	global_load_dwordx4 v[36:39], v6, s[20:21] nt
	s_add_u32 s20, s20, s28
	s_addc_u32 s21, s21, 0
	global_load_dwordx4 v[40:43], v6, s[20:21] nt
	s_add_u32 s20, s20, s28
	s_addc_u32 s21, s21, 0
	global_load_dwordx4 v[44:47], v6, s[20:21] nt
	s_waitcnt vmcnt(14)
	s_branch .Lp0_procb

.Lp0_procb:
	s_cmp_eq_u64 s[32:33], 0
	s_cbranch_scc1 .Lp0_nomul_b
	v_mul_f32_e32 v64, v64, v96
	v_mul_f32_e32 v65, v65, v96
	v_mul_f32_e32 v66, v66, v96
	v_mul_f32_e32 v67, v67, v96
	v_mul_f32_e32 v68, v68, v97
	v_mul_f32_e32 v69, v69, v97
	v_mul_f32_e32 v70, v70, v97
	v_mul_f32_e32 v71, v71, v97
	v_mul_f32_e32 v72, v72, v98
	v_mul_f32_e32 v73, v73, v98
	v_mul_f32_e32 v74, v74, v98
	v_mul_f32_e32 v75, v75, v98
	v_mul_f32_e32 v76, v76, v99
	v_mul_f32_e32 v77, v77, v99
	v_mul_f32_e32 v78, v78, v99
	v_mul_f32_e32 v79, v79, v99
	v_mul_f32_e32 v80, v80, v100
	v_mul_f32_e32 v81, v81, v100
	v_mul_f32_e32 v82, v82, v100
	v_mul_f32_e32 v83, v83, v100
	v_mul_f32_e32 v84, v84, v101
	v_mul_f32_e32 v85, v85, v101
	v_mul_f32_e32 v86, v86, v101
	v_mul_f32_e32 v87, v87, v101
	v_mul_f32_e32 v88, v88, v102
	v_mul_f32_e32 v89, v89, v102
	v_mul_f32_e32 v90, v90, v102
	v_mul_f32_e32 v91, v91, v102
	v_mul_f32_e32 v92, v92, v103
	v_mul_f32_e32 v93, v93, v103
	v_mul_f32_e32 v94, v94, v103
	v_mul_f32_e32 v95, v95, v103
.Lp0_nomul_b:
	v_cvt_pk_bf16_f32 v112, v64, v68
	v_cvt_pk_bf16_f32 v113, v72, v76
	v_cvt_pk_bf16_f32 v114, v80, v84
	v_cvt_pk_bf16_f32 v115, v88, v92
	v_cvt_pk_bf16_f32 v116, v65, v69
	v_cvt_pk_bf16_f32 v117, v73, v77
	v_cvt_pk_bf16_f32 v118, v81, v85
	v_cvt_pk_bf16_f32 v119, v89, v93
	v_cvt_pk_bf16_f32 v120, v66, v70
	v_cvt_pk_bf16_f32 v121, v74, v78
	v_cvt_pk_bf16_f32 v122, v82, v86
	v_cvt_pk_bf16_f32 v123, v90, v94
	v_cvt_pk_bf16_f32 v124, v67, v71
	v_cvt_pk_bf16_f32 v125, v75, v79
	v_cvt_pk_bf16_f32 v126, v83, v87
	v_cvt_pk_bf16_f32 v127, v91, v95
	global_store_dwordx4 v5, v[112:115], s[34:35]
	s_add_u32 s34, s34, 0x1000
	s_addc_u32 s35, s35, 0
	global_store_dwordx4 v5, v[116:119], s[34:35]
	s_add_u32 s34, s34, 0x1000
	s_addc_u32 s35, s35, 0
	global_store_dwordx4 v5, v[120:123], s[34:35]
	s_add_u32 s34, s34, 0x1000
	s_addc_u32 s35, s35, 0
	global_store_dwordx4 v5, v[124:127], s[34:35]
	s_add_u32 s46, s7, s8
	s_cmp_lt_u32 s7, 0xa000
	s_cbranch_scc0 .Lp0_done
	s_cmp_lt_u32 s46, 0xa000
	s_cbranch_scc0 .Lp0_nob
	s_mul_hi_u32 s9, s46, 0x66666667
	s_lshr_b32 s9, s9, 12
	s_mul_i32 s10, s9, 0x2800
	s_sub_u32 s10, s46, s10
	s_sub_u32 s9, 3, s9
	s_cmp_lt_u32 s10, 0x2000
	s_cselect_b64 s[32:33], -1, 0
	s_cselect_b32 s11, 0, 0x2000
	s_cselect_b32 s14, 7, 5
	s_cselect_b32 s15, 15, 13
	s_cselect_b32 s16, 26, 24
	s_cselect_b32 s17, 25, 23
	s_cselect_b32 s38, s84, s92
	s_cselect_b32 s39, s85, s93
	s_cselect_b32 s34, s40, s42
	s_cselect_b32 s35, s41, s43
	s_sub_u32 s10, s10, s11
	s_lshr_b32 s24, s10, 3
	s_lshr_b32 s25, s24, s14
	s_lshl_b32 s26, s25, s14
	s_sub_u32 s24, s24, s26
	s_and_b32 s26, s10, 1
	s_lshl_b32 s24, s24, 1
	s_or_b32 s24, s24, s26
	s_bfe_u32 s26, s10, 0x20001
	s_lshl_b32 s25, s25, 2
	s_or_b32 s25, s25, s26
	s_lshl_b32 s25, s25, 6
	s_lshl_b32 s24, s24, 5
	s_lshl_b32 s26, s9, s16
	s_lshl_b32 s27, s25, s15
	s_add_u32 s26, s26, s27
	s_lshl_b32 s27, s24, 2
	s_add_u32 s26, s26, s27
	s_add_u32 s38, s38, s26
	s_addc_u32 s39, s39, 0
	s_lshl_b32 s29, 1, s15
	s_lshl_b32 s26, s9, s17
	s_lshl_b32 s27, s24, 12
	s_add_u32 s26, s26, s27
	s_lshl_b32 s27, s25, 1
	s_add_u32 s26, s26, s27
	s_add_u32 s34, s34, s26
	s_addc_u32 s35, s35, 0
	s_lshl_b32 s26, s9, 13
	s_lshl_b32 s27, s25, 2
	s_add_u32 s26, s26, s27
	s_add_u32 s44, s82, s26
	s_addc_u32 s45, s83, 0
	v_cndmask_b32_e64 v7, v3, v2, s[32:33]
	global_load_dwordx4 v[96:99], v4, s[44:45]
	global_load_dwordx4 v[100:103], v4, s[44:45] offset:16
	global_load_dwordx4 v[64:67], v7, s[38:39] nt
	s_add_u32 s38, s38, s29
	s_addc_u32 s39, s39, 0
	global_load_dwordx4 v[68:71], v7, s[38:39] nt
	s_add_u32 s38, s38, s29
	s_addc_u32 s39, s39, 0
	global_load_dwordx4 v[72:75], v7, s[38:39] nt
	s_add_u32 s38, s38, s29
	s_addc_u32 s39, s39, 0
	global_load_dwordx4 v[76:79], v7, s[38:39] nt
	s_add_u32 s38, s38, s29
	s_addc_u32 s39, s39, 0
	global_load_dwordx4 v[80:83], v7, s[38:39] nt
	s_add_u32 s38, s38, s29
	s_addc_u32 s39, s39, 0
	global_load_dwordx4 v[84:87], v7, s[38:39] nt
	s_add_u32 s38, s38, s29
	s_addc_u32 s39, s39, 0
	global_load_dwordx4 v[88:91], v7, s[38:39] nt
	s_add_u32 s38, s38, s29
	s_addc_u32 s39, s39, 0
	global_load_dwordx4 v[92:95], v7, s[38:39] nt
	s_waitcnt vmcnt(14)
	s_branch .Lp0_loop
.Lp0_nob:
	s_waitcnt vmcnt(0)
	s_branch .Lp0_loop
.Lp0_done:
.LBB0_20:
	s_load_dword s18, s[0:1], 0x48
	s_cmpk_gt_i32 s6, 0x1fff
	s_cbranch_scc1 .LBB0_25
	v_mbcnt_lo_u32_b32 v2, -1, 0
	v_mbcnt_hi_u32_b32 v2, -1, v2
	v_and_b32_e32 v3, 64, v2
	v_add_u32_e32 v3, 64, v3
	v_xor_b32_e32 v4, 1, v2
	v_cmp_lt_i32_e32 vcc, v4, v3
	s_ashr_i32 s7, s6, 31
	s_lshl_b64 s[10:11], s[6:7], 7
	v_cndmask_b32_e32 v4, v2, v4, vcc
	v_lshlrev_b32_e32 v8, 2, v4
	v_xor_b32_e32 v4, 2, v2
	v_cmp_lt_i32_e32 vcc, v4, v3
	v_mov_b32_e32 v5, 0
	s_ashr_i32 s9, s8, 31
	v_cndmask_b32_e32 v4, v2, v4, vcc
	v_lshlrev_b32_e32 v9, 2, v4
	v_xor_b32_e32 v4, 4, v2
	v_cmp_lt_i32_e32 vcc, v4, v3
	s_lshl_b64 s[12:13], s[6:7], 13
	v_cmp_gt_u32_e64 s[0:1], 32, v1
	v_cndmask_b32_e32 v4, v2, v4, vcc
	v_lshlrev_b32_e32 v10, 2, v4
	v_xor_b32_e32 v4, 8, v2
	v_cmp_lt_i32_e32 vcc, v4, v3
	v_cmp_eq_u32_e64 s[4:5], 0, v1
	s_nop 0
	v_cndmask_b32_e32 v4, v2, v4, vcc
	v_lshlrev_b32_e32 v11, 2, v4
	v_xor_b32_e32 v4, 16, v2
	v_cmp_lt_i32_e32 vcc, v4, v3
	s_nop 1
	v_cndmask_b32_e32 v4, v2, v4, vcc
	v_lshlrev_b32_e32 v12, 2, v4
	v_xor_b32_e32 v4, 32, v2
	v_cmp_lt_i32_e32 vcc, v4, v3
	s_nop 1
	v_cndmask_b32_e32 v2, v2, v4, vcc
	v_lshlrev_b32_e32 v4, 2, v1
	v_lshlrev_b32_e32 v13, 2, v2
	v_lshl_add_u64 v[2:3], s[10:11], 0, v[4:5]
	s_mov_b64 s[10:11], 0x16100000
	v_lshl_add_u64 v[2:3], v[2:3], 0, s[10:11]
	s_lshl_b64 s[10:11], s[8:9], 7
	s_add_u32 s12, s80, s12
	v_lshlrev_b32_e32 v4, 4, v1
	s_addc_u32 s13, s81, s13
	v_lshl_add_u64 v[4:5], s[12:13], 0, v[4:5]
	s_mov_b64 s[12:13], 0x1000
	s_lshl_b64 s[14:15], s[6:7], 12
	v_lshl_add_u64 v[4:5], v[4:5], 0, s[12:13]
	s_lshl_b64 s[12:13], s[8:9], 13
	v_lshl_or_b32 v6, v1, 3, s14
	v_mov_b32_e32 v7, s15
	s_lshl_b64 s[14:15], s[8:9], 12
	s_mov_b32 s7, 0xa100000
	s_branch .LBB0_23
